# combined: v166 + ple prologue hoists + early seam polls + SSM pass-2 row prefetch + SSM stagger of waves 4-7
# baseline (speedup 1.0000x reference)
; #define GAS __attribute__((address_space(1)))
; __device__ __forceinline__ void ssm_phase(Frame& F) {
;     ...
; #pragma unroll 1
;         for (int it = 0; it < 2; ++it) {
;             const int cA = F.wave + 8 * aq + 32 * it;
;             const bf16* arow = ubase + (size_t)(cA * 64 + atk) * SG + 8 * h;
;             bf16x8 afr[8];
; #pragma unroll
;             for (int s = 0; s < 8; ++s) afr[s] = __builtin_nontemporal_load((const GAS bf16x8*)(arow + (size_t)(8 * s) * SG));
.Lstg2:
.LBB0_329:
	s_nop 0
	v_cndmask_b32_e64 v0, 0, 1, s[2:3]
	s_add_i32 s0, s0, s33
	v_cmp_ne_u32_e32 vcc, 1, v0
	s_cmp_eq_u64 s[2:3], 0
	s_cbranch_scc1 .Lssm_it1
	s_waitcnt vmcnt(0)
	v_mov_b32_e32 v16, v216
	v_mov_b32_e32 v17, v217
	v_mov_b32_e32 v18, v218
	v_mov_b32_e32 v19, v219
	v_mov_b32_e32 v120, v220
	v_mov_b32_e32 v121, v221
	v_mov_b32_e32 v122, v222
	v_mov_b32_e32 v123, v223
	v_mov_b32_e32 v116, v224
	v_mov_b32_e32 v117, v225
	v_mov_b32_e32 v118, v226
	v_mov_b32_e32 v119, v227
	v_mov_b32_e32 v112, v228
	v_mov_b32_e32 v113, v229
	v_mov_b32_e32 v114, v230
	v_mov_b32_e32 v115, v231
	v_mov_b32_e32 v108, v232
	v_mov_b32_e32 v109, v233
	v_mov_b32_e32 v110, v234
	v_mov_b32_e32 v111, v235
	v_mov_b32_e32 v104, v236
	v_mov_b32_e32 v105, v237
	v_mov_b32_e32 v106, v238
	v_mov_b32_e32 v107, v239
	v_mov_b32_e32 v100, v240
	v_mov_b32_e32 v101, v241
	v_mov_b32_e32 v102, v242
	v_mov_b32_e32 v103, v243
	v_mov_b32_e32 v96, v248
	v_mov_b32_e32 v97, v249
	v_mov_b32_e32 v98, v250
	v_mov_b32_e32 v99, v251
	s_add_i32 s99, s0, 32
	v_add_u32_e32 v246, s99, v194
	v_lshl_or_b32 v246, v246, 6, v192
	v_mov_b32_e32 v247, 0
	v_lshlrev_b64 v[246:247], 5, v[246:247]
	v_lshl_add_u64 v[246:247], v[124:125], 0, v[246:247]
	global_load_dwordx4 v[216:219], v[246:247], off nt
	global_load_dwordx4 v[220:223], v[246:247], off offset:256 nt
	global_load_dwordx4 v[224:227], v[246:247], off offset:512 nt
	global_load_dwordx4 v[228:231], v[246:247], off offset:768 nt
	global_load_dwordx4 v[232:235], v[246:247], off offset:1024 nt
	global_load_dwordx4 v[236:239], v[246:247], off offset:1280 nt
	global_load_dwordx4 v[240:243], v[246:247], off offset:1536 nt
	global_load_dwordx4 v[248:251], v[246:247], off offset:1792 nt
	s_branch .Lssm_go
